# prep wave setup: 64 LoRA weight rows loaded in one batch per pass instead of 4 serialized batches
# speedup vs baseline: 1.0098x; 1.0098x over previous
.LBB0_581:
	global_load_dword v66, v184, s[0:1]
	s_add_u32 s0, s0, 0x2000
	s_addc_u32 s1, s1, 0
	global_load_dword v67, v184, s[0:1]
	s_add_u32 s0, s0, 0x2000
	s_addc_u32 s1, s1, 0
	global_load_dword v68, v184, s[0:1]
	s_add_u32 s0, s0, 0x2000
	s_addc_u32 s1, s1, 0
	global_load_dword v69, v184, s[0:1]
	s_add_u32 s0, s0, 0x2000
	s_addc_u32 s1, s1, 0
	global_load_dword v70, v184, s[0:1]
	s_add_u32 s0, s0, 0x2000
	s_addc_u32 s1, s1, 0
	global_load_dword v71, v184, s[0:1]
	s_add_u32 s0, s0, 0x2000
	s_addc_u32 s1, s1, 0
	global_load_dword v72, v184, s[0:1]
	s_add_u32 s0, s0, 0x2000
	s_addc_u32 s1, s1, 0
	global_load_dword v73, v184, s[0:1]
	s_add_u32 s0, s0, 0x2000
	s_addc_u32 s1, s1, 0
	global_load_dword v74, v184, s[0:1]
	s_add_u32 s0, s0, 0x2000
	s_addc_u32 s1, s1, 0
	global_load_dword v75, v184, s[0:1]
	s_add_u32 s0, s0, 0x2000
	s_addc_u32 s1, s1, 0
	global_load_dword v76, v184, s[0:1]
	s_add_u32 s0, s0, 0x2000
	s_addc_u32 s1, s1, 0
	global_load_dword v77, v184, s[0:1]
	s_add_u32 s0, s0, 0x2000
	s_addc_u32 s1, s1, 0
	global_load_dword v78, v184, s[0:1]
	s_add_u32 s0, s0, 0x2000
	s_addc_u32 s1, s1, 0
	global_load_dword v79, v184, s[0:1]
	s_add_u32 s0, s0, 0x2000
	s_addc_u32 s1, s1, 0
	global_load_dword v80, v184, s[0:1]
	s_add_u32 s0, s0, 0x2000
	s_addc_u32 s1, s1, 0
	global_load_dword v81, v184, s[0:1]
	s_add_u32 s0, s0, 0x2000
	s_addc_u32 s1, s1, 0
	global_load_dword v82, v184, s[0:1]
	s_add_u32 s0, s0, 0x2000
	s_addc_u32 s1, s1, 0
	global_load_dword v83, v184, s[0:1]
	s_add_u32 s0, s0, 0x2000
	s_addc_u32 s1, s1, 0
	global_load_dword v84, v184, s[0:1]
	s_add_u32 s0, s0, 0x2000
	s_addc_u32 s1, s1, 0
	global_load_dword v85, v184, s[0:1]
	s_add_u32 s0, s0, 0x2000
	s_addc_u32 s1, s1, 0
	global_load_dword v86, v184, s[0:1]
	s_add_u32 s0, s0, 0x2000
	s_addc_u32 s1, s1, 0
	global_load_dword v87, v184, s[0:1]
	s_add_u32 s0, s0, 0x2000
	s_addc_u32 s1, s1, 0
	global_load_dword v88, v184, s[0:1]
	s_add_u32 s0, s0, 0x2000
	s_addc_u32 s1, s1, 0
	global_load_dword v89, v184, s[0:1]
	s_add_u32 s0, s0, 0x2000
	s_addc_u32 s1, s1, 0
	global_load_dword v90, v184, s[0:1]
	s_add_u32 s0, s0, 0x2000
	s_addc_u32 s1, s1, 0
	global_load_dword v91, v184, s[0:1]
	s_add_u32 s0, s0, 0x2000
	s_addc_u32 s1, s1, 0
	global_load_dword v92, v184, s[0:1]
	s_add_u32 s0, s0, 0x2000
	s_addc_u32 s1, s1, 0
	global_load_dword v93, v184, s[0:1]
	s_add_u32 s0, s0, 0x2000
	s_addc_u32 s1, s1, 0
	global_load_dword v94, v184, s[0:1]
	s_add_u32 s0, s0, 0x2000
	s_addc_u32 s1, s1, 0
	global_load_dword v95, v184, s[0:1]
	s_add_u32 s0, s0, 0x2000
	s_addc_u32 s1, s1, 0
	global_load_dword v96, v184, s[0:1]
	s_add_u32 s0, s0, 0x2000
	s_addc_u32 s1, s1, 0
	global_load_dword v97, v184, s[0:1]
	s_add_u32 s0, s0, 0x2000
	s_addc_u32 s1, s1, 0
	global_load_dword v98, v184, s[0:1]
	s_add_u32 s0, s0, 0x2000
	s_addc_u32 s1, s1, 0
	global_load_dword v99, v184, s[0:1]
	s_add_u32 s0, s0, 0x2000
	s_addc_u32 s1, s1, 0
	global_load_dword v100, v184, s[0:1]
	s_add_u32 s0, s0, 0x2000
	s_addc_u32 s1, s1, 0
	global_load_dword v101, v184, s[0:1]
	s_add_u32 s0, s0, 0x2000
	s_addc_u32 s1, s1, 0
	global_load_dword v102, v184, s[0:1]
	s_add_u32 s0, s0, 0x2000
	s_addc_u32 s1, s1, 0
	global_load_dword v103, v184, s[0:1]
	s_add_u32 s0, s0, 0x2000
	s_addc_u32 s1, s1, 0
	global_load_dword v104, v184, s[0:1]
	s_add_u32 s0, s0, 0x2000
	s_addc_u32 s1, s1, 0
	global_load_dword v105, v184, s[0:1]
	s_add_u32 s0, s0, 0x2000
	s_addc_u32 s1, s1, 0
	global_load_dword v106, v184, s[0:1]
	s_add_u32 s0, s0, 0x2000
	s_addc_u32 s1, s1, 0
	global_load_dword v107, v184, s[0:1]
	s_add_u32 s0, s0, 0x2000
	s_addc_u32 s1, s1, 0
	global_load_dword v108, v184, s[0:1]
	s_add_u32 s0, s0, 0x2000
	s_addc_u32 s1, s1, 0
	global_load_dword v109, v184, s[0:1]
	s_add_u32 s0, s0, 0x2000
	s_addc_u32 s1, s1, 0
	global_load_dword v110, v184, s[0:1]
	s_add_u32 s0, s0, 0x2000
	s_addc_u32 s1, s1, 0
	global_load_dword v111, v184, s[0:1]
	s_add_u32 s0, s0, 0x2000
	s_addc_u32 s1, s1, 0
	global_load_dword v112, v184, s[0:1]
	s_add_u32 s0, s0, 0x2000
	s_addc_u32 s1, s1, 0
	global_load_dword v113, v184, s[0:1]
	s_add_u32 s0, s0, 0x2000
	s_addc_u32 s1, s1, 0
	global_load_dword v114, v184, s[0:1]
	s_add_u32 s0, s0, 0x2000
	s_addc_u32 s1, s1, 0
	global_load_dword v115, v184, s[0:1]
	s_add_u32 s0, s0, 0x2000
	s_addc_u32 s1, s1, 0
	global_load_dword v130, v184, s[0:1]
	s_add_u32 s0, s0, 0x2000
	s_addc_u32 s1, s1, 0
	global_load_dword v131, v184, s[0:1]
	s_add_u32 s0, s0, 0x2000
	s_addc_u32 s1, s1, 0
	global_load_dword v132, v184, s[0:1]
	s_add_u32 s0, s0, 0x2000
	s_addc_u32 s1, s1, 0
	global_load_dword v133, v184, s[0:1]
	s_add_u32 s0, s0, 0x2000
	s_addc_u32 s1, s1, 0
	global_load_dword v134, v184, s[0:1]
	s_add_u32 s0, s0, 0x2000
	s_addc_u32 s1, s1, 0
	global_load_dword v135, v184, s[0:1]
	s_add_u32 s0, s0, 0x2000
	s_addc_u32 s1, s1, 0
	global_load_dword v136, v184, s[0:1]
	s_add_u32 s0, s0, 0x2000
	s_addc_u32 s1, s1, 0
	global_load_dword v137, v184, s[0:1]
	s_add_u32 s0, s0, 0x2000
	s_addc_u32 s1, s1, 0
	global_load_dword v138, v184, s[0:1]
	s_add_u32 s0, s0, 0x2000
	s_addc_u32 s1, s1, 0
	global_load_dword v139, v184, s[0:1]
	s_add_u32 s0, s0, 0x2000
	s_addc_u32 s1, s1, 0
	global_load_dword v140, v184, s[0:1]
	s_add_u32 s0, s0, 0x2000
	s_addc_u32 s1, s1, 0
	global_load_dword v141, v184, s[0:1]
	s_add_u32 s0, s0, 0x2000
	s_addc_u32 s1, s1, 0
	global_load_dword v142, v184, s[0:1]
	s_add_u32 s0, s0, 0x2000
	s_addc_u32 s1, s1, 0
	global_load_dword v143, v184, s[0:1]
	s_waitcnt vmcnt(0)
	v_cvt_pk_bf16_f32 v144, v66, v67
	v_cvt_pk_bf16_f32 v145, v68, v69
	v_cvt_pk_bf16_f32 v146, v70, v71
	v_cvt_pk_bf16_f32 v147, v72, v73
	v_cvt_pk_bf16_f32 v148, v74, v75
	v_cvt_pk_bf16_f32 v149, v76, v77
	v_cvt_pk_bf16_f32 v150, v78, v79
	v_cvt_pk_bf16_f32 v151, v80, v81
	v_cvt_pk_bf16_f32 v152, v82, v83
	v_cvt_pk_bf16_f32 v153, v84, v85
	v_cvt_pk_bf16_f32 v154, v86, v87
	v_cvt_pk_bf16_f32 v155, v88, v89
	v_cvt_pk_bf16_f32 v156, v90, v91
	v_cvt_pk_bf16_f32 v157, v92, v93
	v_cvt_pk_bf16_f32 v158, v94, v95
	v_cvt_pk_bf16_f32 v159, v96, v97
	v_cvt_pk_bf16_f32 v160, v98, v99
	v_cvt_pk_bf16_f32 v161, v100, v101
	v_cvt_pk_bf16_f32 v162, v102, v103
	v_cvt_pk_bf16_f32 v163, v104, v105
	v_cvt_pk_bf16_f32 v164, v106, v107
	v_cvt_pk_bf16_f32 v165, v108, v109
	v_cvt_pk_bf16_f32 v166, v110, v111
	v_cvt_pk_bf16_f32 v167, v112, v113
	v_cvt_pk_bf16_f32 v168, v114, v115
	v_cvt_pk_bf16_f32 v169, v130, v131
	v_cvt_pk_bf16_f32 v170, v132, v133
	v_cvt_pk_bf16_f32 v171, v134, v135
	v_cvt_pk_bf16_f32 v172, v136, v137
	v_cvt_pk_bf16_f32 v173, v138, v139
	v_cvt_pk_bf16_f32 v174, v140, v141
	v_cvt_pk_bf16_f32 v175, v142, v143
	ds_write_b128 v207, v[144:147]
	ds_write_b128 v207, v[148:151] offset:16
	ds_write_b128 v207, v[152:155] offset:32
	ds_write_b128 v207, v[156:159] offset:48
	ds_write_b128 v207, v[160:163] offset:64
	ds_write_b128 v207, v[164:167] offset:80
	ds_write_b128 v207, v[168:171] offset:96
	ds_write_b128 v207, v[172:175] offset:112
	s_waitcnt lgkmcnt(0)
	ds_read_b128 v[32:35], v193
	ds_read_b128 v[36:39], v193 offset:64
	ds_read_b128 v[52:55], v193 offset:2304
	ds_read_b128 v[40:43], v193 offset:2368
	ds_read_b128 v[56:59], v193 offset:4608
	ds_read_b128 v[44:47], v193 offset:4672
	ds_read_b128 v[60:63], v193 offset:6912
	ds_read_b128 v[48:51], v193 offset:6976
	s_waitcnt lgkmcnt(0)
	s_mov_b64 s[38:39], 0
	s_and_b64 vcc, exec, s[36:37]
	s_cbranch_vccnz .LBB0_584
	s_waitcnt lgkmcnt(7)
	v_mov_b64_e32 v[0:1], v[32:33]
	s_waitcnt lgkmcnt(5)
	v_mov_b64_e32 v[4:5], v[52:53]
	s_waitcnt lgkmcnt(3)
	v_mov_b64_e32 v[8:9], v[56:57]
	s_waitcnt lgkmcnt(1)
	v_mov_b64_e32 v[12:13], v[60:61]
	v_mov_b64_e32 v[16:17], v[36:37]
	v_mov_b64_e32 v[20:21], v[40:41]
	v_mov_b64_e32 v[24:25], v[44:45]
	s_waitcnt lgkmcnt(0)
	v_mov_b64_e32 v[28:29], v[48:49]
	v_mov_b64_e32 v[2:3], v[34:35]
	v_mov_b64_e32 v[6:7], v[54:55]
	v_mov_b64_e32 v[10:11], v[58:59]
	v_mov_b64_e32 v[14:15], v[62:63]
	v_mov_b64_e32 v[18:19], v[38:39]
	v_mov_b64_e32 v[22:23], v[42:43]
	v_mov_b64_e32 v[26:27], v[46:47]
	v_mov_b64_e32 v[30:31], v[50:51]
	s_branch .LBB0_580
